# v24_toep
# speedup vs baseline: 1.0353x; 1.0087x over previous
; __device__ __forceinline__ void hyena_item(const Params& p, int layer, int c, bf16_t* sm) {
;     ...
;     const bf16_t* gU = WSB(U) + (size_t)((1024 * (o + 1) + c) * 4) * LP + (size_t)ob * LP + ot;
;     u32x2 gw[5];
; #pragma unroll
;     for (int tt = 0; tt < 5; ++tt) {
;       const int Tt = wave + 8 * tt;
;       gw[tt] = u32x2{0u, 0u};
;       if (Tt <= 32 && 64 * Tt + ot < L) gw[tt] = *(const u32x2*)(gU + 64 * Tt);
;     }
.LBB0_519:
	s_or_b64 exec, exec, s[0:1]
	v_readlane_b32 s0, v254, 6
	s_waitcnt vmcnt(0)
	v_and_b32_e32 v12, 3, v114
	v_readlane_b32 s1, v254, 7
	v_mul_u32_u24_e32 v0, 0x840, v12
	v_bfe_u32 v13, v114, 4, 2
	v_add_u32_e32 v6, 0x1000, v81
	v_mov_b64_e32 v[2:3], s[0:1]
	v_and_or_b32 v5, v114, 12, v13
	v_mad_i64_i32 v[2:3], s[0:1], v6, s66, v[2:3]
	v_lshlrev_b32_e32 v112, 1, v0
	v_mov_b32_e32 v113, v1
	v_lshlrev_b32_e32 v179, 2, v5
	v_ashrrev_i32_e32 v4, 6, v114
	v_lshl_add_u64 v[2:3], v[2:3], 0, v[112:113]
	v_lshlrev_b32_e32 v0, 3, v5
	v_lshlrev_b32_e32 v102, 8, v4
	v_lshl_add_u64 v[2:3], v[2:3], 0, v[0:1]
	v_cmp_gt_i32_e64 s[14:15], 33, v4
	v_mov_b32_e32 v122, 0
	v_or_b32_e32 v180, v179, v102
	v_mov_b32_e32 v126, 0
	v_mov_b32_e32 v127, 0
	s_and_saveexec_b64 s[6:7], s[14:15]
	s_cbranch_execz .LBB0_523
	v_cmp_gt_i32_e64 s[0:1], s69, v180
	v_mov_b32_e32 v127, 0
	v_mov_b32_e32 v126, 0
	s_and_saveexec_b64 s[8:9], s[0:1]
	s_cbranch_execz .LBB0_522
	v_ashrrev_i32_e32 v103, 31, v102
	v_lshl_add_u64 v[6:7], v[102:103], 1, v[2:3]
	global_load_dwordx2 v[126:127], v[6:7], off

; __device__ __forceinline__ void hyena_item(const Params& p, int layer, int c, bf16_t* sm) {
;     ...
;     const bf16_t* gU = WSB(U) + (size_t)((1024 * (o + 1) + c) * 4) * LP + (size_t)ob * LP + ot;
;     u32x2 gw[5];
; #pragma unroll
;     for (int tt = 0; tt < 5; ++tt) {
;       const int Tt = wave + 8 * tt;
;       gw[tt] = u32x2{0u, 0u};
;       if (Tt <= 32 && 64 * Tt + ot < L) gw[tt] = *(const u32x2*)(gU + 64 * Tt);
;     }
.LBB0_523:
	s_or_b64 exec, exec, s[6:7]
	v_lshl_add_u32 v189, v4, 2, 1
	v_lshlrev_b32_e32 v104, 6, v189
	v_cmp_gt_i32_e64 s[12:13], 25, v4
	v_or_b32_e32 v181, v179, v104
	v_mov_b32_e32 v123, 0
	s_and_saveexec_b64 s[6:7], s[12:13]
	s_cbranch_execz .LBB0_527
	v_cmp_gt_i32_e64 s[0:1], s69, v181
	v_mov_b32_e32 v123, 0
	v_mov_b32_e32 v122, 0
	s_and_saveexec_b64 s[8:9], s[0:1]
	s_cbranch_execz .LBB0_526
	v_ashrrev_i32_e32 v105, 31, v104
	v_lshl_add_u64 v[6:7], v[104:105], 1, v[2:3]
	global_load_dwordx2 v[122:123], v[6:7], off

; __device__ __forceinline__ void hyena_item(const Params& p, int layer, int c, bf16_t* sm) {
;     ...
;     const bf16_t* gU = WSB(U) + (size_t)((1024 * (o + 1) + c) * 4) * LP + (size_t)ob * LP + ot;
;     u32x2 gw[5];
; #pragma unroll
;     for (int tt = 0; tt < 5; ++tt) {
;       const int Tt = wave + 8 * tt;
;       gw[tt] = u32x2{0u, 0u};
;       if (Tt <= 32 && 64 * Tt + ot < L) gw[tt] = *(const u32x2*)(gU + 64 * Tt);
;     }
.LBB0_527:
	s_or_b64 exec, exec, s[6:7]
	v_lshl_add_u32 v113, v4, 2, 2
	v_lshlrev_b32_e32 v106, 6, v113
	v_cmp_gt_i32_e64 s[10:11], 17, v4
	v_mov_b32_e32 v118, 0
	v_or_b32_e32 v182, v179, v106
	v_mov_b32_e32 v124, 0
	v_mov_b32_e32 v125, 0
	s_and_saveexec_b64 s[6:7], s[10:11]
	s_cbranch_execz .LBB0_531
	v_cmp_gt_i32_e64 s[0:1], s69, v182
	v_mov_b32_e32 v125, 0
	v_mov_b32_e32 v124, 0
	s_and_saveexec_b64 s[8:9], s[0:1]
	s_cbranch_execz .LBB0_530
	v_ashrrev_i32_e32 v107, 31, v106
	v_lshl_add_u64 v[6:7], v[106:107], 1, v[2:3]
	global_load_dwordx2 v[124:125], v[6:7], off

; __device__ __forceinline__ void hyena_item(const Params& p, int layer, int c, bf16_t* sm) {
;     ...
;     const bf16_t* gU = WSB(U) + (size_t)((1024 * (o + 1) + c) * 4) * LP + (size_t)ob * LP + ot;
;     u32x2 gw[5];
; #pragma unroll
;     for (int tt = 0; tt < 5; ++tt) {
;       const int Tt = wave + 8 * tt;
;       gw[tt] = u32x2{0u, 0u};
;       if (Tt <= 32 && 64 * Tt + ot < L) gw[tt] = *(const u32x2*)(gU + 64 * Tt);
;     }
.LBB0_531:
	s_or_b64 exec, exec, s[6:7]
	v_lshl_add_u32 v105, v4, 2, 3
	v_lshlrev_b32_e32 v108, 6, v105
	v_cmp_gt_i32_e64 s[8:9], 9, v4
	v_or_b32_e32 v183, v179, v108
	v_mov_b32_e32 v119, 0
	s_and_saveexec_b64 s[6:7], s[8:9]
	s_cbranch_execz .LBB0_535
	v_cmp_gt_i32_e64 s[0:1], s69, v183
	v_mov_b32_e32 v119, 0
	v_mov_b32_e32 v118, 0
	s_and_saveexec_b64 s[64:65], s[0:1]
	s_cbranch_execz .LBB0_534
	v_ashrrev_i32_e32 v109, 31, v108
	v_lshl_add_u64 v[6:7], v[108:109], 1, v[2:3]
	global_load_dwordx2 v[118:119], v[6:7], off

; __device__ __forceinline__ void hyena_item(const Params& p, int layer, int c, bf16_t* sm) {
;     ...
;     const bf16_t* gU = WSB(U) + (size_t)((1024 * (o + 1) + c) * 4) * LP + (size_t)ob * LP + ot;
;     u32x2 gw[5];
; #pragma unroll
;     for (int tt = 0; tt < 5; ++tt) {
;       const int Tt = wave + 8 * tt;
;       gw[tt] = u32x2{0u, 0u};
;       if (Tt <= 32 && 64 * Tt + ot < L) gw[tt] = *(const u32x2*)(gU + 64 * Tt);
;     }
.LBB0_535:
	s_or_b64 exec, exec, s[6:7]
	v_lshl_add_u32 v103, v4, 2, 4
	v_lshlrev_b32_e32 v110, 6, v103
	v_cmp_lt_i32_e64 s[6:7], 6, v4
	v_mov_b32_e32 v4, 0
	v_or_b32_e32 v184, v179, v110
	v_mov_b32_e32 v120, 0
	v_mov_b32_e32 v121, 0
	s_and_saveexec_b64 s[64:65], s[6:7]
	s_cbranch_execz .LBB0_539
	v_cmp_gt_i32_e64 s[0:1], s69, v184
	v_mov_b32_e32 v121, 0
	v_mov_b32_e32 v120, 0
	s_and_saveexec_b64 s[4:5], s[0:1]
	s_cbranch_execz .LBB0_538
	v_ashrrev_i32_e32 v111, 31, v110
	v_lshl_add_u64 v[2:3], v[110:111], 1, v[2:3]
	global_load_dwordx2 v[120:121], v[2:3], off

; #define SCHED() __builtin_amdgcn_sched_barrier(0)
; #define HY_LOAD(AF, BF, i) do { const int dp_ = 64 - 32 * (i); \
;       BF = *(const bf16x8*)(zfrag - dp_); \
;       _Pragma("unroll") for (int tt = 0; tt < 4; ++tt) AF[tt] = *(const bf16x8*)(abase - (dp_ + 64 * (wave + 8 * tt)) * 2); \
;       if (has5) AF[4] = *(const bf16x8*)(abase - (dp_ + 64 * 32) * 2); } while (0)
; #define HY_MMA(AF, BF) do { \
;       _Pragma("unroll") for (int tt = 0; tt < 4; ++tt) acc[tt] = mfma16(AF[tt], BF, acc[tt]); \
;       if (has5) acc[4] = mfma16(AF[4], BF, acc[4]); } while (0)
; __device__ __forceinline__ void hyena_item(const Params& p, int layer, int c, bf16_t* sm) {
;     ...
;   const int s0c = (8 - (l15 & 7)) & 7;
;   const char* abase = smc + hy_copy_base(s0c) + (GTC - l15 + 8 * quad - s0c) * 2;
;   const bf16_t* zfrag = zb + (l15 & 3) * ZS + ZM + 16 * (l15 >> 2) + 8 * quad;
;   const int ob = l15 & 3, ot = 16 * (l15 >> 2) + quad * 4;
;     ...
;     f32x4 acc[5];
; #pragma unroll
;     for (int tt = 0; tt < 5; ++tt) acc[tt] = f32x4{0.f, 0.f, 0.f, 0.f};
;     const bool has5 = (wave == 0);
;     ...
;     bf16x8 a0[5], a1[5], b0, b1;
;     a0[4] = bf16x8{0, 0, 0, 0, 0, 0, 0, 0}; a1[4] = a0[4];
;     HY_LOAD(a0, b0, 0);
;     for (int i = 0; i < 66; i += 2) {
;       HY_LOAD(a1, b1, i + 1);
;       SCHED();
;       HY_MMA(a0, b0);
;       SCHED();
;       HY_LOAD(a0, b0, i + 2);
;       SCHED();
;       HY_MMA(a1, b1);
;       SCHED();
;     }
.LBB0_543:
	s_or_b64 exec, exec, s[0:1]
	v_sub_u32_e32 v0, 0, v114
	v_and_b32_e32 v0, 7, v0
	v_and_b32_e32 v14, 15, v114
	v_cmp_ne_u32_e32 vcc, 0, v0
	v_add_u32_e32 v21, v0, v14
	v_mul_u32_u24_e32 v15, 0x2200, v0
	v_lshlrev_b32_e32 v2, 2, v0
	v_mov_b32_e32 v20, 0xeda87430
	v_lshrrev_b32_e32 v20, v2, v20
	v_and_b32_e32 v20, 15, v20
	v_lshlrev_b32_e32 v20, 4, v20
	v_lshlrev_b32_e32 v2, 3, v13
	v_sub_u32_e32 v0, v2, v21
	v_lshlrev_b32_e32 v0, 1, v0
	v_add3_u32 v186, v20, v15, v0
	v_lshlrev_b32_e32 v0, 3, v114
	v_mul_u32_u24_e32 v128, 0x11a0, v12
	v_and_b32_e32 v0, 0x60, v0
	v_lshlrev_b32_e32 v13, 4, v13
	v_add3_u32 v187, v128, v0, v13
	v_not_b32_e32 v0, v114
	v_lshlrev_b32_e32 v0, 1, v0
	v_and_b32_e32 v0, 0xffffff80, v0
	v_add_u32_e32 v188, v186, v0
	s_waitcnt lgkmcnt(0)
	s_barrier
	v_mul_u32_u24_e32 v115, 0x810, v12
	v_add3_u32 v12, v20, v15, v13
	v_lshlrev_b32_e32 v15, 1, v21
	v_sub_u32_e32 v12, v12, v15
	v_add_u32_e32 v129, 0x4880, v12
	v_lshlrev_b32_e32 v12, 3, v14
	v_and_b32_e32 v12, 0x60, v12
	v_add_u32_e32 v12, v128, v12
	s_movk_i32 s0, 0x80
	v_add3_u32 v130, v12, v13, s0
	v_mov_b32_e32 v2, v1
	v_mov_b32_e32 v3, v1
	v_mov_b32_e32 v0, v1
	v_ashrrev_i32_e32 v117, 31, v116
	v_readlane_b32 s100, v253, 37
	v_readlane_b32 s101, v253, 38
	s_nop 4
	v_lshl_add_u64 v[248:249], v[116:117], 2, s[100:101]
	s_movk_i32 s100, 0x1000
	s_mov_b32 s101, 0
	global_load_dword v252, v[248:249], off
	v_lshl_add_u64 v[246:247], v[248:249], 0, s[100:101]
	s_nop 0
	global_load_dword v245, v[246:247], off
	v_lshrrev_b32_e32 v237, 6, v114
	s_nop 1
	v_readfirstlane_b32 s100, v237
	s_lshl_b32 s101, s100, 9
	v_subrev_u32_e32 v235, s101, v129
	v_add_u32_e32 v235, 0xdc0, v235
	v_add_u32_e32 v236, 0xffffffc0, v130
	s_nop 0
	ds_read_b128 v[72:75], v236
	ds_read_b128 v[76:79], v236 offset:64
	ds_read_b128 v[24:27], v235
	ds_read_b128 v[56:59], v235 offset:64
	ds_read_b128 v[32:35], v235 offset:128
	ds_read_b128 v[60:63], v235 offset:192
	ds_read_b128 v[44:47], v235 offset:256
	ds_read_b128 v[64:67], v235 offset:320
	ds_read_b128 v[48:51], v235 offset:384
	ds_read_b128 v[68:71], v235 offset:448
	ds_read_b128 v[16:19], v235 offset:512
	ds_read_b128 v[52:55], v235 offset:576
	v_mov_b32_e32 v40, 0
	v_mov_b32_e32 v41, 0
	v_mov_b32_e32 v42, 0
	v_mov_b32_e32 v43, 0
	v_mov_b32_e32 v36, 0
	v_mov_b32_e32 v37, 0
	v_mov_b32_e32 v38, 0
	v_mov_b32_e32 v39, 0
	v_mov_b32_e32 v28, 0
	v_mov_b32_e32 v29, 0
	v_mov_b32_e32 v30, 0
	v_mov_b32_e32 v31, 0
	v_mov_b32_e32 v20, 0
	v_mov_b32_e32 v21, 0
	v_mov_b32_e32 v22, 0
	v_mov_b32_e32 v23, 0
	v_mov_b32_e32 v12, 0
	v_mov_b32_e32 v13, 0
	v_mov_b32_e32 v14, 0
	v_mov_b32_e32 v15, 0
	v_add_u32_e32 v235, 0x280, v235
	v_add_u32_e32 v236, 0x80, v236
	s_mov_b32 s101, 0
	s_waitcnt lgkmcnt(0)
.Lmy_hy0_loop:
	s_waitcnt lgkmcnt(2)
	v_mfma_f32_16x16x32_bf16 v[40:43], v[16:19], v[72:75], v[40:43]
	v_mfma_f32_16x16x32_bf16 v[36:39], v[48:51], v[72:75], v[36:39]
	v_mfma_f32_16x16x32_bf16 v[28:31], v[44:47], v[72:75], v[28:31]
	v_mfma_f32_16x16x32_bf16 v[20:23], v[32:35], v[72:75], v[20:23]
	s_cmp_lg_u32 s100, 7
	s_cbranch_scc1 .Lmy_hy0_l0
	v_mfma_f32_16x16x32_bf16 v[12:15], v[24:27], v[72:75], v[12:15]
.Lmy_hy0_l0:
	ds_read_b128 v[24:27], v235
	ds_read_b128 v[72:75], v236
	s_waitcnt lgkmcnt(2)
	v_mfma_f32_16x16x32_bf16 v[40:43], v[52:55], v[76:79], v[40:43]
	v_mfma_f32_16x16x32_bf16 v[36:39], v[68:71], v[76:79], v[36:39]
	v_mfma_f32_16x16x32_bf16 v[28:31], v[64:67], v[76:79], v[28:31]
	v_mfma_f32_16x16x32_bf16 v[20:23], v[60:63], v[76:79], v[20:23]
	s_cmp_lg_u32 s100, 7
	s_cbranch_scc1 .Lmy_hy0_l1
	v_mfma_f32_16x16x32_bf16 v[12:15], v[56:59], v[76:79], v[12:15]
.Lmy_hy0_l1:
	ds_read_b128 v[56:59], v235 offset:64
	ds_read_b128 v[76:79], v236 offset:64
	s_waitcnt lgkmcnt(2)
	v_mfma_f32_16x16x32_bf16 v[40:43], v[24:27], v[72:75], v[40:43]
	v_mfma_f32_16x16x32_bf16 v[36:39], v[16:19], v[72:75], v[36:39]
	v_mfma_f32_16x16x32_bf16 v[28:31], v[48:51], v[72:75], v[28:31]
	v_mfma_f32_16x16x32_bf16 v[20:23], v[44:47], v[72:75], v[20:23]
	s_cmp_lg_u32 s100, 7
	s_cbranch_scc1 .Lmy_hy0_l2
	v_mfma_f32_16x16x32_bf16 v[12:15], v[32:35], v[72:75], v[12:15]
; #define SCHED() __builtin_amdgcn_sched_barrier(0)
; #define HY_LOAD(AF, BF, i) do { const int dp_ = 64 - 32 * (i); \
;       BF = *(const bf16x8*)(zfrag - dp_); \
;       _Pragma("unroll") for (int tt = 0; tt < 4; ++tt) AF[tt] = *(const bf16x8*)(abase - (dp_ + 64 * (wave + 8 * tt)) * 2); \
;       if (has5) AF[4] = *(const bf16x8*)(abase - (dp_ + 64 * 32) * 2); } while (0)
; #define HY_MMA(AF, BF) do { \
;       _Pragma("unroll") for (int tt = 0; tt < 4; ++tt) acc[tt] = mfma16(AF[tt], BF, acc[tt]); \
;       if (has5) acc[4] = mfma16(AF[4], BF, acc[4]); } while (0)
; __device__ __forceinline__ void hyena_item(const Params& p, int layer, int c, bf16_t* sm) {
;     ...
;     bf16x8 a0[5], a1[5], b0, b1;
;     a0[4] = bf16x8{0, 0, 0, 0, 0, 0, 0, 0}; a1[4] = a0[4];
;     HY_LOAD(a0, b0, 0);
;     for (int i = 0; i < 66; i += 2) {
;       HY_LOAD(a1, b1, i + 1);
;       SCHED();
;       HY_MMA(a0, b0);
;       SCHED();
;       HY_LOAD(a0, b0, i + 2);
;       SCHED();
;       HY_MMA(a1, b1);
;       SCHED();
;     }
.Lmy_hy0_l2:
	ds_read_b128 v[32:35], v235 offset:128
	ds_read_b128 v[72:75], v236 offset:128
	s_waitcnt lgkmcnt(2)
	v_mfma_f32_16x16x32_bf16 v[40:43], v[56:59], v[76:79], v[40:43]
	v_mfma_f32_16x16x32_bf16 v[36:39], v[52:55], v[76:79], v[36:39]
	v_mfma_f32_16x16x32_bf16 v[28:31], v[68:71], v[76:79], v[28:31]
	v_mfma_f32_16x16x32_bf16 v[20:23], v[64:67], v[76:79], v[20:23]
	s_cmp_lg_u32 s100, 7
	s_cbranch_scc1 .Lmy_hy0_l3
	v_mfma_f32_16x16x32_bf16 v[12:15], v[60:63], v[76:79], v[12:15]
.Lmy_hy0_l3:
	ds_read_b128 v[60:63], v235 offset:192
	ds_read_b128 v[76:79], v236 offset:192
	s_waitcnt lgkmcnt(2)
	v_mfma_f32_16x16x32_bf16 v[40:43], v[32:35], v[72:75], v[40:43]
	v_mfma_f32_16x16x32_bf16 v[36:39], v[24:27], v[72:75], v[36:39]
	v_mfma_f32_16x16x32_bf16 v[28:31], v[16:19], v[72:75], v[28:31]
	v_mfma_f32_16x16x32_bf16 v[20:23], v[48:51], v[72:75], v[20:23]
	s_cmp_lg_u32 s100, 7
	s_cbranch_scc1 .Lmy_hy0_l4
	v_mfma_f32_16x16x32_bf16 v[12:15], v[44:47], v[72:75], v[12:15]
.Lmy_hy0_l4:
	ds_read_b128 v[44:47], v235 offset:256
	ds_read_b128 v[72:75], v236 offset:256
	s_waitcnt lgkmcnt(2)
	v_mfma_f32_16x16x32_bf16 v[40:43], v[60:63], v[76:79], v[40:43]
	v_mfma_f32_16x16x32_bf16 v[36:39], v[56:59], v[76:79], v[36:39]
	v_mfma_f32_16x16x32_bf16 v[28:31], v[52:55], v[76:79], v[28:31]
	v_mfma_f32_16x16x32_bf16 v[20:23], v[68:71], v[76:79], v[20:23]
	s_cmp_lg_u32 s100, 7
	s_cbranch_scc1 .Lmy_hy0_l5
	v_mfma_f32_16x16x32_bf16 v[12:15], v[64:67], v[76:79], v[12:15]
.Lmy_hy0_l5:
	ds_read_b128 v[64:67], v235 offset:320
	ds_read_b128 v[76:79], v236 offset:320
	s_waitcnt lgkmcnt(2)
	v_mfma_f32_16x16x32_bf16 v[40:43], v[44:47], v[72:75], v[40:43]
	v_mfma_f32_16x16x32_bf16 v[36:39], v[32:35], v[72:75], v[36:39]
	v_mfma_f32_16x16x32_bf16 v[28:31], v[24:27], v[72:75], v[28:31]
	v_mfma_f32_16x16x32_bf16 v[20:23], v[16:19], v[72:75], v[20:23]
	s_cmp_lg_u32 s100, 7
	s_cbranch_scc1 .Lmy_hy0_l6
	v_mfma_f32_16x16x32_bf16 v[12:15], v[48:51], v[72:75], v[12:15]
.Lmy_hy0_l6:
	ds_read_b128 v[48:51], v235 offset:384
	ds_read_b128 v[72:75], v236 offset:384
	s_waitcnt lgkmcnt(2)
	v_mfma_f32_16x16x32_bf16 v[40:43], v[64:67], v[76:79], v[40:43]
	v_mfma_f32_16x16x32_bf16 v[36:39], v[60:63], v[76:79], v[36:39]
	v_mfma_f32_16x16x32_bf16 v[28:31], v[56:59], v[76:79], v[28:31]
	v_mfma_f32_16x16x32_bf16 v[20:23], v[52:55], v[76:79], v[20:23]
	s_cmp_lg_u32 s100, 7
	s_cbranch_scc1 .Lmy_hy0_l7
	v_mfma_f32_16x16x32_bf16 v[12:15], v[68:71], v[76:79], v[12:15]
.Lmy_hy0_l7:
	ds_read_b128 v[68:71], v235 offset:448
	ds_read_b128 v[76:79], v236 offset:448
	s_waitcnt lgkmcnt(2)
	v_mfma_f32_16x16x32_bf16 v[40:43], v[48:51], v[72:75], v[40:43]
	v_mfma_f32_16x16x32_bf16 v[36:39], v[44:47], v[72:75], v[36:39]
	v_mfma_f32_16x16x32_bf16 v[28:31], v[32:35], v[72:75], v[28:31]
	v_mfma_f32_16x16x32_bf16 v[20:23], v[24:27], v[72:75], v[20:23]
	s_cmp_lg_u32 s100, 7
	s_cbranch_scc1 .Lmy_hy0_l8
	v_mfma_f32_16x16x32_bf16 v[12:15], v[16:19], v[72:75], v[12:15]
.Lmy_hy0_l8:
	ds_read_b128 v[16:19], v235 offset:512
	ds_read_b128 v[72:75], v236 offset:512
	s_waitcnt lgkmcnt(2)
	v_mfma_f32_16x16x32_bf16 v[40:43], v[68:71], v[76:79], v[40:43]
	v_mfma_f32_16x16x32_bf16 v[36:39], v[64:67], v[76:79], v[36:39]
	v_mfma_f32_16x16x32_bf16 v[28:31], v[60:63], v[76:79], v[28:31]
	v_mfma_f32_16x16x32_bf16 v[20:23], v[56:59], v[76:79], v[20:23]
	s_cmp_lg_u32 s100, 7
	s_cbranch_scc1 .Lmy_hy0_l9
	v_mfma_f32_16x16x32_bf16 v[12:15], v[52:55], v[76:79], v[12:15]
.Lmy_hy0_l9:
	ds_read_b128 v[52:55], v235 offset:576
	ds_read_b128 v[76:79], v236 offset:576
	v_add_u32_e32 v235, 0x280, v235
	v_add_u32_e32 v236, 0x280, v236
	s_add_i32 s101, s101, 1
	s_cmp_lt_u32 s101, 6
	s_cbranch_scc1 .Lmy_hy0_loop
	s_waitcnt lgkmcnt(2)
	v_mfma_f32_16x16x32_bf16 v[40:43], v[16:19], v[72:75], v[40:43]
	v_mfma_f32_16x16x32_bf16 v[36:39], v[48:51], v[72:75], v[36:39]
	v_mfma_f32_16x16x32_bf16 v[28:31], v[44:47], v[72:75], v[28:31]
	v_mfma_f32_16x16x32_bf16 v[20:23], v[32:35], v[72:75], v[20:23]
	s_cmp_lg_u32 s100, 7
	s_cbranch_scc1 .Lmy_hy0_t0
	v_mfma_f32_16x16x32_bf16 v[12:15], v[24:27], v[72:75], v[12:15]

; __device__ __forceinline__ float bflo(unsigned w) { return __uint_as_float(w << 16); }
; __device__ __forceinline__ float bfhi(unsigned w) { return __uint_as_float(w & 0xffff0000u); }
; #define HY_MMA(AF, BF) do { \
;       _Pragma("unroll") for (int tt = 0; tt < 4; ++tt) acc[tt] = mfma16(AF[tt], BF, acc[tt]); \
;       if (has5) acc[4] = mfma16(AF[4], BF, acc[4]); } while (0)
; __device__ __forceinline__ void hyena_item(const Params& p, int layer, int c, bf16_t* sm) {
;     ...
;     HY_MMA(a0, b0);
;     ...
;     __syncthreads();
;     const float sk = p.b_skip[(layer * 2 + o) * 1024 + c];
; #pragma unroll
;     for (int tt = 0; tt < 5; ++tt) {
;       const int Tt = wave + 8 * tt;
;       if (Tt <= 32) {
;         int t = 64 * Tt + ot;
;         if (t < L) {
;           u32x2 zw = *(const u32x2*)(zb + ob * ZS + ZM + t);
;           float v0 = bflo(gw[tt].x) * (acc[tt][0] + sk * bflo(zw.x));
;           float v1 = bfhi(gw[tt].x) * (acc[tt][1] + sk * bfhi(zw.x));
;           float v2 = bflo(gw[tt].y) * (acc[tt][2] + sk * bflo(zw.y));
;           float v3 = bfhi(gw[tt].y) * (acc[tt][3] + sk * bfhi(zw.y));
.Lmy_hy0_t5:
	s_waitcnt lgkmcnt(0)
	v_mfma_f32_16x16x32_bf16 v[40:43], v[44:47], v[72:75], v[40:43]
	v_mfma_f32_16x16x32_bf16 v[36:39], v[32:35], v[72:75], v[36:39]
	v_mfma_f32_16x16x32_bf16 v[28:31], v[24:27], v[72:75], v[28:31]
	v_mfma_f32_16x16x32_bf16 v[20:23], v[16:19], v[72:75], v[20:23]
	s_cmp_lg_u32 s100, 7
	s_cbranch_scc1 .Lmy_hy0_t6
	v_mfma_f32_16x16x32_bf16 v[12:15], v[48:51], v[72:75], v[12:15]
.Lmy_hy0_t6:
	s_nop 7
	v_readlane_b32 s72, v253, 23
	v_readlane_b32 s86, v253, 37
	v_readlane_b32 s87, v253, 38
	s_barrier
	s_nop 0
	v_lshl_add_u64 v[70:71], v[116:117], 2, s[86:87]
	s_waitcnt vmcnt(0)
	v_mov_b32_e32 v0, v252
	v_lshrrev_b32_e32 v185, 6, v114
	v_lshl_or_b32 v185, v185, 8, v179
	v_readlane_b32 s73, v253, 24
	v_readlane_b32 s74, v253, 25
	v_readlane_b32 s75, v253, 26
	v_readlane_b32 s76, v253, 27
	v_readlane_b32 s77, v253, 28
	v_readlane_b32 s78, v253, 29
	v_readlane_b32 s79, v253, 30
	v_readlane_b32 s80, v253, 31
	v_readlane_b32 s81, v253, 32
	v_readlane_b32 s82, v253, 33
	v_readlane_b32 s83, v253, 34
	v_readlane_b32 s84, v253, 35
	v_readlane_b32 s85, v253, 36
	s_and_saveexec_b64 s[30:31], s[14:15]
	s_cbranch_execz .LBB0_560
	v_cmp_gt_i32_e64 s[0:1], s69, v185
	s_and_b64 exec, exec, s[0:1]
	s_cbranch_execz .LBB0_560
	v_lshl_add_u32 v16, v185, 1, v128
	ds_read_b64 v[2:3], v16 offset:192
	s_waitcnt lgkmcnt(0)
	v_and_b32_e32 v17, 0xffff0000, v3
	v_lshlrev_b32_e32 v3, 16, v3
	v_and_b32_e32 v18, 0xffff0000, v2
	v_lshlrev_b32_e32 v2, 16, v2
	s_waitcnt vmcnt(0)
	v_fmac_f32_e32 v42, v0, v3
	v_lshlrev_b32_e32 v3, 16, v127
	v_fmac_f32_e32 v40, v0, v2
	v_lshlrev_b32_e32 v2, 16, v126
	v_fmac_f32_e32 v43, v0, v17
	v_and_b32_e32 v17, 0xffff0000, v127
	v_mul_f32_e32 v3, v42, v3
	v_fmac_f32_e32 v41, v0, v18
	v_and_b32_e32 v18, 0xffff0000, v126
	v_mul_f32_e32 v2, v40, v2
	v_mul_f32_e32 v17, v43, v17
	v_mul_f32_e32 v18, v41, v18
	v_cvt_pk_bf16_f32 v2, v2, v18
	v_cvt_pk_bf16_f32 v3, v3, v17
	ds_write_b64 v16, v[2:3] offset:192

; #define SCHED() __builtin_amdgcn_sched_barrier(0)
; #define HY_LOAD(AF, BF, i) do { const int dp_ = 64 - 32 * (i); \
;       BF = *(const bf16x8*)(zfrag - dp_); \
;       _Pragma("unroll") for (int tt = 0; tt < 4; ++tt) AF[tt] = *(const bf16x8*)(abase - (dp_ + 64 * (wave + 8 * tt)) * 2); \
;       if (has5) AF[4] = *(const bf16x8*)(abase - (dp_ + 64 * 32) * 2); } while (0)
; #define HY_MMA(AF, BF) do { \
;       _Pragma("unroll") for (int tt = 0; tt < 4; ++tt) acc[tt] = mfma16(AF[tt], BF, acc[tt]); \
;       if (has5) acc[4] = mfma16(AF[4], BF, acc[4]); } while (0)
; __device__ __forceinline__ void hyena_item(const Params& p, int layer, int c, bf16_t* sm) {
;     ...
;     __syncthreads();
;     f32x4 acc[5];
; #pragma unroll
;     for (int tt = 0; tt < 5; ++tt) acc[tt] = f32x4{0.f, 0.f, 0.f, 0.f};
;     const bool has5 = (wave == 0);
;     ...
;     bf16x8 a0[5], a1[5], b0, b1;
;     a0[4] = bf16x8{0, 0, 0, 0, 0, 0, 0, 0}; a1[4] = a0[4];
;     HY_LOAD(a0, b0, 0);
;     for (int i = 0; i < 66; i += 2) {
;       HY_LOAD(a1, b1, i + 1);
;       SCHED();
;       HY_MMA(a0, b0);
;       SCHED();
;       HY_LOAD(a0, b0, i + 2);
;       SCHED();
;       HY_MMA(a1, b1);
;       SCHED();
;     }
.LBB0_607:
	s_or_b64 exec, exec, s[16:17]
	s_barrier
	v_mov_b32_e32 v0, v1
	s_lshl_b32 s101, s100, 9
	v_subrev_u32_e32 v235, s101, v129
	v_add_u32_e32 v235, 0xdc0, v235
	v_add_u32_e32 v236, 0xffffffc0, v130
	s_nop 0
	ds_read_b128 v[62:65], v236
	ds_read_b128 v[66:69], v236 offset:64
	ds_read_b128 v[14:17], v235
	ds_read_b128 v[46:49], v235 offset:64
	ds_read_b128 v[22:25], v235 offset:128
	ds_read_b128 v[50:53], v235 offset:192
	ds_read_b128 v[34:37], v235 offset:256
	ds_read_b128 v[54:57], v235 offset:320
	ds_read_b128 v[38:41], v235 offset:384
	ds_read_b128 v[58:61], v235 offset:448
	ds_read_b128 v[10:13], v235 offset:512
	ds_read_b128 v[42:45], v235 offset:576
	v_mov_b32_e32 v30, 0
	v_mov_b32_e32 v31, 0
	v_mov_b32_e32 v32, 0
	v_mov_b32_e32 v33, 0
	v_mov_b32_e32 v26, 0
	v_mov_b32_e32 v27, 0
	v_mov_b32_e32 v28, 0
	v_mov_b32_e32 v29, 0
	v_mov_b32_e32 v18, 0
	v_mov_b32_e32 v19, 0
	v_mov_b32_e32 v20, 0
	v_mov_b32_e32 v21, 0
	v_mov_b32_e32 v6, 0
	v_mov_b32_e32 v7, 0
	v_mov_b32_e32 v8, 0
	v_mov_b32_e32 v9, 0
	v_mov_b32_e32 v2, 0
	v_mov_b32_e32 v3, 0
	v_mov_b32_e32 v4, 0
	v_mov_b32_e32 v5, 0
	v_add_u32_e32 v235, 0x280, v235
	v_add_u32_e32 v236, 0x80, v236
	s_mov_b32 s101, 0
	s_waitcnt lgkmcnt(0)
.Lmy_hy1_loop:
	s_waitcnt lgkmcnt(2)
	v_mfma_f32_16x16x32_bf16 v[30:33], v[10:13], v[62:65], v[30:33]
	v_mfma_f32_16x16x32_bf16 v[26:29], v[38:41], v[62:65], v[26:29]
	v_mfma_f32_16x16x32_bf16 v[18:21], v[34:37], v[62:65], v[18:21]
	v_mfma_f32_16x16x32_bf16 v[6:9], v[22:25], v[62:65], v[6:9]
	s_cmp_lg_u32 s100, 7
	s_cbranch_scc1 .Lmy_hy1_l0
	v_mfma_f32_16x16x32_bf16 v[2:5], v[14:17], v[62:65], v[2:5]
.Lmy_hy1_l0:
	ds_read_b128 v[14:17], v235
	ds_read_b128 v[62:65], v236
	s_waitcnt lgkmcnt(2)
	v_mfma_f32_16x16x32_bf16 v[30:33], v[42:45], v[66:69], v[30:33]
	v_mfma_f32_16x16x32_bf16 v[26:29], v[58:61], v[66:69], v[26:29]
	v_mfma_f32_16x16x32_bf16 v[18:21], v[54:57], v[66:69], v[18:21]
	v_mfma_f32_16x16x32_bf16 v[6:9], v[50:53], v[66:69], v[6:9]
	s_cmp_lg_u32 s100, 7
	s_cbranch_scc1 .Lmy_hy1_l1
	v_mfma_f32_16x16x32_bf16 v[2:5], v[46:49], v[66:69], v[2:5]
.Lmy_hy1_l1:
	ds_read_b128 v[46:49], v235 offset:64
	ds_read_b128 v[66:69], v236 offset:64
	s_waitcnt lgkmcnt(2)
	v_mfma_f32_16x16x32_bf16 v[30:33], v[14:17], v[62:65], v[30:33]
	v_mfma_f32_16x16x32_bf16 v[26:29], v[10:13], v[62:65], v[26:29]
	v_mfma_f32_16x16x32_bf16 v[18:21], v[38:41], v[62:65], v[18:21]
	v_mfma_f32_16x16x32_bf16 v[6:9], v[34:37], v[62:65], v[6:9]
	s_cmp_lg_u32 s100, 7
	s_cbranch_scc1 .Lmy_hy1_l2
	v_mfma_f32_16x16x32_bf16 v[2:5], v[22:25], v[62:65], v[2:5]
.Lmy_hy1_l2:
	ds_read_b128 v[22:25], v235 offset:128
	ds_read_b128 v[62:65], v236 offset:128
	s_waitcnt lgkmcnt(2)
	v_mfma_f32_16x16x32_bf16 v[30:33], v[46:49], v[66:69], v[30:33]
	v_mfma_f32_16x16x32_bf16 v[26:29], v[42:45], v[66:69], v[26:29]
	v_mfma_f32_16x16x32_bf16 v[18:21], v[58:61], v[66:69], v[18:21]
	v_mfma_f32_16x16x32_bf16 v[6:9], v[54:57], v[66:69], v[6:9]
	s_cmp_lg_u32 s100, 7
	s_cbranch_scc1 .Lmy_hy1_l3
	v_mfma_f32_16x16x32_bf16 v[2:5], v[50:53], v[66:69], v[2:5]
.Lmy_hy1_l3:
	ds_read_b128 v[50:53], v235 offset:192
	ds_read_b128 v[66:69], v236 offset:192
	s_waitcnt lgkmcnt(2)
	v_mfma_f32_16x16x32_bf16 v[30:33], v[22:25], v[62:65], v[30:33]
	v_mfma_f32_16x16x32_bf16 v[26:29], v[14:17], v[62:65], v[26:29]
	v_mfma_f32_16x16x32_bf16 v[18:21], v[10:13], v[62:65], v[18:21]
	v_mfma_f32_16x16x32_bf16 v[6:9], v[38:41], v[62:65], v[6:9]
	s_cmp_lg_u32 s100, 7
	s_cbranch_scc1 .Lmy_hy1_l4
	v_mfma_f32_16x16x32_bf16 v[2:5], v[34:37], v[62:65], v[2:5]
.Lmy_hy1_l4:
	ds_read_b128 v[34:37], v235 offset:256
	ds_read_b128 v[62:65], v236 offset:256
	s_waitcnt lgkmcnt(2)
	v_mfma_f32_16x16x32_bf16 v[30:33], v[50:53], v[66:69], v[30:33]
	v_mfma_f32_16x16x32_bf16 v[26:29], v[46:49], v[66:69], v[26:29]
	v_mfma_f32_16x16x32_bf16 v[18:21], v[42:45], v[66:69], v[18:21]
	v_mfma_f32_16x16x32_bf16 v[6:9], v[58:61], v[66:69], v[6:9]
	s_cmp_lg_u32 s100, 7
	s_cbranch_scc1 .Lmy_hy1_l5
	v_mfma_f32_16x16x32_bf16 v[2:5], v[54:57], v[66:69], v[2:5]
.Lmy_hy1_l5:
	ds_read_b128 v[54:57], v235 offset:320
	ds_read_b128 v[66:69], v236 offset:320
	s_waitcnt lgkmcnt(2)
	v_mfma_f32_16x16x32_bf16 v[30:33], v[34:37], v[62:65], v[30:33]
	v_mfma_f32_16x16x32_bf16 v[26:29], v[22:25], v[62:65], v[26:29]
	v_mfma_f32_16x16x32_bf16 v[18:21], v[14:17], v[62:65], v[18:21]
	v_mfma_f32_16x16x32_bf16 v[6:9], v[10:13], v[62:65], v[6:9]
	s_cmp_lg_u32 s100, 7
	s_cbranch_scc1 .Lmy_hy1_l6
	v_mfma_f32_16x16x32_bf16 v[2:5], v[38:41], v[62:65], v[2:5]
.Lmy_hy1_l6:
	ds_read_b128 v[38:41], v235 offset:384
	ds_read_b128 v[62:65], v236 offset:384
	s_waitcnt lgkmcnt(2)
	v_mfma_f32_16x16x32_bf16 v[30:33], v[54:57], v[66:69], v[30:33]
	v_mfma_f32_16x16x32_bf16 v[26:29], v[50:53], v[66:69], v[26:29]
	v_mfma_f32_16x16x32_bf16 v[18:21], v[46:49], v[66:69], v[18:21]
	v_mfma_f32_16x16x32_bf16 v[6:9], v[42:45], v[66:69], v[6:9]
	s_cmp_lg_u32 s100, 7
	s_cbranch_scc1 .Lmy_hy1_l7
	v_mfma_f32_16x16x32_bf16 v[2:5], v[58:61], v[66:69], v[2:5]
.Lmy_hy1_l7:
	ds_read_b128 v[58:61], v235 offset:448
	ds_read_b128 v[66:69], v236 offset:448
	s_waitcnt lgkmcnt(2)
	v_mfma_f32_16x16x32_bf16 v[30:33], v[38:41], v[62:65], v[30:33]
	v_mfma_f32_16x16x32_bf16 v[26:29], v[34:37], v[62:65], v[26:29]
	v_mfma_f32_16x16x32_bf16 v[18:21], v[22:25], v[62:65], v[18:21]
	v_mfma_f32_16x16x32_bf16 v[6:9], v[14:17], v[62:65], v[6:9]
	s_cmp_lg_u32 s100, 7
	s_cbranch_scc1 .Lmy_hy1_l8
	v_mfma_f32_16x16x32_bf16 v[2:5], v[10:13], v[62:65], v[2:5]
.Lmy_hy1_l8:
	ds_read_b128 v[10:13], v235 offset:512
	ds_read_b128 v[62:65], v236 offset:512
	s_waitcnt lgkmcnt(2)
	v_mfma_f32_16x16x32_bf16 v[30:33], v[58:61], v[66:69], v[30:33]
	v_mfma_f32_16x16x32_bf16 v[26:29], v[54:57], v[66:69], v[26:29]
	v_mfma_f32_16x16x32_bf16 v[18:21], v[50:53], v[66:69], v[18:21]
	v_mfma_f32_16x16x32_bf16 v[6:9], v[46:49], v[66:69], v[6:9]
	s_cmp_lg_u32 s100, 7
	s_cbranch_scc1 .Lmy_hy1_l9
	v_mfma_f32_16x16x32_bf16 v[2:5], v[42:45], v[66:69], v[2:5]
.Lmy_hy1_l9:
	ds_read_b128 v[42:45], v235 offset:576
	ds_read_b128 v[66:69], v236 offset:576
	v_add_u32_e32 v235, 0x280, v235
	v_add_u32_e32 v236, 0x280, v236
	s_add_i32 s101, s101, 1
	s_cmp_lt_u32 s101, 6
	s_cbranch_scc1 .Lmy_hy1_loop
	s_waitcnt lgkmcnt(2)
	v_mfma_f32_16x16x32_bf16 v[30:33], v[10:13], v[62:65], v[30:33]
	v_mfma_f32_16x16x32_bf16 v[26:29], v[38:41], v[62:65], v[26:29]
	v_mfma_f32_16x16x32_bf16 v[18:21], v[34:37], v[62:65], v[18:21]
	v_mfma_f32_16x16x32_bf16 v[6:9], v[22:25], v[62:65], v[6:9]
	s_cmp_lg_u32 s100, 7
	s_cbranch_scc1 .Lmy_hy1_t0
	v_mfma_f32_16x16x32_bf16 v[2:5], v[14:17], v[62:65], v[2:5]

; __device__ __forceinline__ float bflo(unsigned w) { return __uint_as_float(w << 16); }
; __device__ __forceinline__ float bfhi(unsigned w) { return __uint_as_float(w & 0xffff0000u); }
; #define HY_MMA(AF, BF) do { \
;       _Pragma("unroll") for (int tt = 0; tt < 4; ++tt) acc[tt] = mfma16(AF[tt], BF, acc[tt]); \
;       if (has5) acc[4] = mfma16(AF[4], BF, acc[4]); } while (0)
; __device__ __forceinline__ void hyena_item(const Params& p, int layer, int c, bf16_t* sm) {
;     ...
;     HY_MMA(a0, b0);
;     ...
;     __syncthreads();
;     const float sk = p.b_skip[(layer * 2 + o) * 1024 + c];
; #pragma unroll
;     for (int tt = 0; tt < 5; ++tt) {
;       const int Tt = wave + 8 * tt;
;       if (Tt <= 32) {
;         int t = 64 * Tt + ot;
;         if (t < L) {
;           u32x2 zw = *(const u32x2*)(zb + ob * ZS + ZM + t);
;           float v0 = bflo(gw[tt].x) * (acc[tt][0] + sk * bflo(zw.x));
;           float v1 = bfhi(gw[tt].x) * (acc[tt][1] + sk * bfhi(zw.x));
;           float v2 = bflo(gw[tt].y) * (acc[tt][2] + sk * bflo(zw.y));
;           float v3 = bfhi(gw[tt].y) * (acc[tt][3] + sk * bfhi(zw.y));
;           if (o == 0) {
;             u32x2 nz = {pack2(v0, v1), pack2(v2, v3)};
;             *(u32x2*)(zb + ob * ZS + ZM + t) = nz;
;           } else {
;             bf16_t* yb = WSH(YB) + (size_t)(ob * L + t) * 1024 + c;
;             const unsigned y01 = pack2(v0, v1), y23 = pack2(v2, v3);
;             yb[0] = (bf16_t)(y01 & 0xffffu); yb[1024] = (bf16_t)(y01 >> 16); yb[2048] = (bf16_t)(y23 & 0xffffu); yb[3072] = (bf16_t)(y23 >> 16);
;           }
.Lmy_hy1_t5:
	s_waitcnt lgkmcnt(0)
	v_mfma_f32_16x16x32_bf16 v[30:33], v[34:37], v[62:65], v[30:33]
	v_mfma_f32_16x16x32_bf16 v[26:29], v[22:25], v[62:65], v[26:29]
	v_mfma_f32_16x16x32_bf16 v[18:21], v[14:17], v[62:65], v[18:21]
	v_mfma_f32_16x16x32_bf16 v[6:9], v[10:13], v[62:65], v[6:9]
	s_cmp_lg_u32 s100, 7
	s_cbranch_scc1 .Lmy_hy1_t6
	v_mfma_f32_16x16x32_bf16 v[2:5], v[38:41], v[62:65], v[2:5]
.Lmy_hy1_t6:
	s_nop 7
	v_add_co_u32_e32 v10, vcc, 0x1000, v70
	s_nop 1
	v_addc_co_u32_e32 v11, vcc, 0, v71, vcc
	s_barrier
	s_waitcnt vmcnt(0)
	v_mov_b32_e32 v0, v245
	v_ashrrev_i32_e32 v81, 31, v80
	s_and_saveexec_b64 s[0:1], s[14:15]
	s_cbranch_execz .LBB0_624
	v_cmp_gt_i32_e32 vcc, s69, v185
	s_and_b64 exec, exec, vcc
	s_cbranch_execz .LBB0_624
	v_lshl_add_u32 v10, v185, 1, v128
	ds_read_b64 v[10:11], v10 offset:192
	v_readlane_b32 s4, v254, 26
	v_readlane_b32 s5, v254, 27
	s_waitcnt lgkmcnt(0)
	v_and_b32_e32 v12, 0xffff0000, v11
	v_lshlrev_b32_e32 v11, 16, v11
	s_waitcnt vmcnt(0)
	v_fmac_f32_e32 v32, v0, v11
	v_lshlrev_b32_e32 v11, 16, v83
	v_mul_f32_e32 v13, v32, v11
	v_and_b32_e32 v11, 0xffff0000, v10
	v_lshlrev_b32_e32 v10, 16, v10
	v_fmac_f32_e32 v30, v0, v10
	v_lshlrev_b32_e32 v10, 16, v82
	v_fmac_f32_e32 v31, v0, v11
	v_and_b32_e32 v11, 0xffff0000, v82
	v_mul_f32_e32 v15, v30, v10
	v_add_u32_e32 v10, v185, v115
	v_mul_f32_e32 v14, v31, v11
	v_ashrrev_i32_e32 v11, 31, v10
	v_lshlrev_b64 v[10:11], 11, v[10:11]
	v_fmac_f32_e32 v33, v0, v12
	v_and_b32_e32 v12, 0xffff0000, v83
	v_lshl_add_u64 v[10:11], s[4:5], 0, v[10:11]
	v_mul_f32_e32 v12, v33, v12
	v_lshl_add_u64 v[10:11], v[80:81], 1, v[10:11]
	v_cvt_pk_bf16_f32 v14, v15, v14
	v_cvt_pk_bf16_f32 v12, v13, v12
	global_store_short v[10:11], v14, off
	global_store_short_d16_hi v[10:11], v14, off offset:2048
	v_add_co_u32_e32 v10, vcc, 0x1000, v10
	s_nop 1
	v_addc_co_u32_e32 v11, vcc, 0, v11, vcc
	global_store_short v[10:11], v12, off
	global_store_short_d16_hi v[10:11], v12, off offset:2048
